# NSA gates prefetched one stage ahead; cg grid sync after phase 0 replaced by XCD barrier
# baseline (speedup 1.0000x reference)
.LBB0_56:
	v_lshrrev_b32_e32 v2, 20, v0
	v_lshrrev_b32_e32 v0, 10, v0
	v_or_b32_e32 v0, v0, v2
	s_movk_i32 s0, 0x3ff
	v_and_or_b32 v0, v0, s0, v1
	v_cmp_eq_u32_e32 vcc, 0, v0
	s_barrier
	s_and_saveexec_b64 s[0:1], vcc
	s_branch .LBB0_66
	buffer_wbl2 sc1
	s_waitcnt vmcnt(0)
	s_load_dwordx2 s[4:5], s[14:15], 0x58
	v_mov_b32_e32 v2, 0
	s_mov_b64 s[6:7], exec
	v_mbcnt_lo_u32_b32 v1, s6, 0
	v_mbcnt_hi_u32_b32 v1, s7, v1
	s_waitcnt lgkmcnt(0)
	global_load_dword v0, v2, s[4:5] offset:40
	v_cmp_eq_u32_e32 vcc, 0, v1
	s_and_saveexec_b64 s[8:9], vcc
	s_cbranch_execz .LBB0_59
	s_bcnt1_i32_b64 s6, s[6:7]
	v_mov_b32_e32 v3, s6
	global_atomic_add v3, v2, v3, s[4:5] offset:32 sc0

.LBB0_70:
	v_readlane_b32 s0, v253, 2
	v_readlane_b32 s1, v253, 3
	v_mov_b32_e32 v1, v0
	v_writelane_b32 v254, s0, 21
	s_load_dwordx4 s[64:67], s[0:1], 0xb0
	s_mov_b32 s81, s80
	v_mbcnt_lo_u32_b32 v1, -1, v1
	v_writelane_b32 v254, s1, 22
	v_mbcnt_hi_u32_b32 v1, -1, v1
	v_readlane_b32 s0, v253, 5
	s_cmp_lt_u32 s92, 1
	s_nop 0
	v_or_b32_e32 v170, s0, v1
	v_readlane_b32 s0, v253, 0
	s_mov_b32 s83, s0
	v_readlane_b32 s1, v253, 1
	s_cbranch_scc1 .LBB0_124
	s_waitcnt vmcnt(0)
	v_cmp_eq_u32_e32 vcc, 0, v170
	s_waitcnt lgkmcnt(0)
	s_barrier
	s_and_saveexec_b64 s[0:1], vcc
	s_cbranch_execz .LBB0_123
	v_readlane_b32 s2, v254, 17
	s_waitcnt vmcnt(0) expcnt(0) lgkmcnt(0)
	s_nop 0
	v_mov_b32_e32 v1, s2
	ds_read_b32 v3, v1
	v_readlane_b32 s2, v254, 18
	s_waitcnt lgkmcnt(0)
	v_cmp_ne_u32_e32 vcc, 0, v3
	v_mov_b32_e32 v1, s2
	ds_read_b32 v2, v1
	s_cbranch_vccnz .LBB0_87
	s_mov_b32 s8, 1
	s_branch .LBB0_75

.LBB0_216:
	s_waitcnt vmcnt(0) lgkmcnt(0)
	s_barrier
	v_mov_b32_e32 v2, v169
	ds_bpermute_b32 v1, v150, v89
	v_mov_b32_e32 v127, v0
	v_readlane_b32 s88, v255, 5
	s_movk_i32 s82, 0x1800
	s_mov_b64 s[84:85], 0x80
	s_waitcnt lgkmcnt(0)
	v_add_f32_e32 v1, v89, v1
	v_max_f32_e32 v1, 0xda24260, v1
	v_readlane_b32 s89, v255, 6
	v_readlane_b32 s87, v255, 0
	v_readlane_b32 s8, v255, 3
	v_readlane_b32 s9, v255, 4
	v_readlane_b32 s83, v255, 2
	v_readlane_b32 s90, v255, 7
	v_readlane_b32 s91, v255, 8
	ds_read2st64_b32 v[8:9], v156 offset0:2 offset1:3
	s_waitcnt vmcnt(0)
	v_div_scale_f32 v3, s[0:1], v1, v1, v2
	v_rcp_f32_e32 v4, v3
	v_readlane_b32 s0, v254, 47
	v_readlane_b32 s1, v254, 48
	v_fma_f32 v5, -v3, v4, 1.0
	v_fmac_f32_e32 v4, v5, v4
	v_div_scale_f32 v5, vcc, v2, v1, v2
	v_mul_f32_e32 v6, v5, v4
	v_fma_f32 v7, -v3, v6, v5
	v_fmac_f32_e32 v6, v7, v4
	v_fma_f32 v3, -v3, v6, v5
	v_div_fmas_f32 v3, v3, v4, v6
	ds_read2st64_b32 v[6:7], v156 offset1:1
	v_div_fixup_f32 v2, v3, v1, v2
	v_lshl_add_u64 v[4:5], s[0:1], 0, v[120:121]
	s_waitcnt lgkmcnt(1)
	v_pk_fma_f32 v[8:9], v[34:35], v[2:3], v[8:9] op_sel_hi:[1,0,1]
	v_lshl_add_u64 v[4:5], v[4:5], 0, v[126:127]
	s_waitcnt lgkmcnt(0)
	v_pk_fma_f32 v[6:7], v[32:33], v[2:3], v[6:7] op_sel_hi:[1,0,1]
	s_nop 0
	v_cvt_pk_bf16_f32 v6, v6, v7
	v_cvt_pk_bf16_f32 v7, v8, v9
	v_lshlrev_b32_e32 v8, 1, v116
	v_mov_b32_e32 v9, v0
	v_lshl_add_u64 v[4:5], v[4:5], 0, v[8:9]
	global_store_dwordx2 v[4:5], v[6:7], off
	ds_read2st64_b32 v[6:7], v156 offset0:4 offset1:5
	ds_read2st64_b32 v[8:9], v156 offset0:6 offset1:7
	s_waitcnt lgkmcnt(1)
	v_pk_fma_f32 v[6:7], v[36:37], v[2:3], v[6:7] op_sel_hi:[1,0,1]
	s_waitcnt lgkmcnt(0)
	v_pk_fma_f32 v[8:9], v[38:39], v[2:3], v[8:9] op_sel_hi:[1,0,1]
	v_cvt_pk_bf16_f32 v6, v6, v7
	v_cvt_pk_bf16_f32 v7, v8, v9
	global_store_dwordx2 v[4:5], v[6:7], off offset:16
	ds_read2st64_b32 v[6:7], v156 offset0:8 offset1:9
	ds_read2st64_b32 v[8:9], v156 offset0:10 offset1:11
	s_waitcnt lgkmcnt(1)
	v_pk_fma_f32 v[6:7], v[40:41], v[2:3], v[6:7] op_sel_hi:[1,0,1]
	s_waitcnt lgkmcnt(0)
	v_pk_fma_f32 v[8:9], v[42:43], v[2:3], v[8:9] op_sel_hi:[1,0,1]
	v_cvt_pk_bf16_f32 v6, v6, v7
	v_cvt_pk_bf16_f32 v7, v8, v9
	global_store_dwordx2 v[4:5], v[6:7], off offset:32
	ds_read2st64_b32 v[6:7], v156 offset0:12 offset1:13
	ds_read2st64_b32 v[8:9], v156 offset0:14 offset1:15
	s_waitcnt lgkmcnt(1)
	v_pk_fma_f32 v[6:7], v[44:45], v[2:3], v[6:7] op_sel_hi:[1,0,1]
	s_waitcnt lgkmcnt(0)
	v_pk_fma_f32 v[8:9], v[46:47], v[2:3], v[8:9] op_sel_hi:[1,0,1]
	v_cvt_pk_bf16_f32 v6, v6, v7
	v_cvt_pk_bf16_f32 v7, v8, v9
	global_store_dwordx2 v[4:5], v[6:7], off offset:48
	ds_read2st64_b32 v[6:7], v156 offset0:16 offset1:17
	ds_read2st64_b32 v[8:9], v156 offset0:18 offset1:19
	s_waitcnt lgkmcnt(1)
	v_pk_fma_f32 v[6:7], v[16:17], v[2:3], v[6:7] op_sel_hi:[1,0,1]
	s_waitcnt lgkmcnt(0)
	v_pk_fma_f32 v[8:9], v[18:19], v[2:3], v[8:9] op_sel_hi:[1,0,1]
	v_cvt_pk_bf16_f32 v6, v6, v7
	v_cvt_pk_bf16_f32 v7, v8, v9
	global_store_dwordx2 v[4:5], v[6:7], off offset:64
	ds_read2st64_b32 v[6:7], v156 offset0:20 offset1:21
	ds_read2st64_b32 v[8:9], v156 offset0:22 offset1:23
	s_waitcnt lgkmcnt(1)
	v_pk_fma_f32 v[6:7], v[20:21], v[2:3], v[6:7] op_sel_hi:[1,0,1]
	s_waitcnt lgkmcnt(0)
	v_pk_fma_f32 v[8:9], v[22:23], v[2:3], v[8:9] op_sel_hi:[1,0,1]
	v_cvt_pk_bf16_f32 v6, v6, v7
	v_cvt_pk_bf16_f32 v7, v8, v9
	global_store_dwordx2 v[4:5], v[6:7], off offset:80
	ds_read2st64_b32 v[6:7], v156 offset0:24 offset1:25
	ds_read2st64_b32 v[8:9], v156 offset0:26 offset1:27
	s_waitcnt lgkmcnt(1)
	v_pk_fma_f32 v[6:7], v[24:25], v[2:3], v[6:7] op_sel_hi:[1,0,1]
	s_waitcnt lgkmcnt(0)
	v_pk_fma_f32 v[8:9], v[26:27], v[2:3], v[8:9] op_sel_hi:[1,0,1]
	v_cvt_pk_bf16_f32 v6, v6, v7
	v_cvt_pk_bf16_f32 v7, v8, v9
	global_store_dwordx2 v[4:5], v[6:7], off offset:96
	ds_read2st64_b32 v[6:7], v156 offset0:28 offset1:29
	ds_read2st64_b32 v[8:9], v156 offset0:30 offset1:31
	s_waitcnt lgkmcnt(1)
	v_pk_fma_f32 v[6:7], v[28:29], v[2:3], v[6:7] op_sel_hi:[1,0,1]
	s_waitcnt lgkmcnt(0)
	v_pk_fma_f32 v[2:3], v[30:31], v[2:3], v[8:9] op_sel_hi:[1,0,1]
	v_cvt_pk_bf16_f32 v6, v6, v7
	v_cvt_pk_bf16_f32 v7, v2, v3
	global_store_dwordx2 v[4:5], v[6:7], off offset:112

.LBB0_313:
	v_readlane_b32 s0, v254, 45
	v_readlane_b32 s1, v254, 46
	s_movk_i32 s2, 0xc0
	v_lshlrev_b32_e32 v4, 2, v99
	v_mov_b64_e32 v[2:3], s[0:1]
	v_mad_u64_u32 v[2:3], s[0:1], v100, s2, v[2:3]
	v_mad_i32_i24 v3, v101, s2, v3
	v_mov_b32_e32 v5, v0
	v_lshl_add_u64 v[124:125], v[2:3], 0, v[4:5]
	s_waitcnt vmcnt(0) lgkmcnt(0)
	s_barrier
	global_load_dword v1, v[124:125], off
	global_load_dword v169, v[124:125], off offset:64
	s_waitcnt vmcnt(1)
	v_mul_f32_e32 v2, v32, v1
	v_mul_f32_e32 v3, v16, v1
	v_mul_f32_e32 v4, v33, v1
	v_mul_f32_e32 v5, v17, v1
	v_mul_f32_e32 v6, v34, v1
	v_mul_f32_e32 v7, v18, v1
	v_mul_f32_e32 v8, v35, v1
	v_mul_f32_e32 v9, v19, v1
	v_mul_f32_e32 v10, v36, v1
	v_mul_f32_e32 v11, v20, v1
	v_mul_f32_e32 v12, v37, v1
	v_mul_f32_e32 v13, v21, v1
	v_mul_f32_e32 v14, v38, v1
	v_mul_f32_e32 v15, v22, v1
	v_mul_f32_e32 v16, v39, v1
	v_mul_f32_e32 v17, v23, v1
	v_mul_f32_e32 v18, v40, v1
	v_mul_f32_e32 v19, v24, v1
	v_mul_f32_e32 v20, v41, v1
	v_mul_f32_e32 v21, v25, v1
	v_mul_f32_e32 v22, v42, v1
	v_mul_f32_e32 v23, v26, v1
	v_mul_f32_e32 v24, v43, v1
	v_mul_f32_e32 v25, v27, v1
	v_mul_f32_e32 v26, v44, v1
	v_mul_f32_e32 v27, v28, v1
	v_mul_f32_e32 v28, v45, v1
	v_mul_f32_e32 v29, v29, v1
	v_mul_f32_e32 v32, v46, v1
	v_mul_f32_e32 v30, v30, v1
	v_mul_f32_e32 v33, v47, v1
	v_mul_f32_e32 v1, v31, v1
	ds_write2st64_b32 v157, v2, v4 offset1:1
	ds_write2st64_b32 v157, v3, v5 offset0:16 offset1:17
	ds_write2st64_b32 v157, v6, v8 offset0:2 offset1:3
	ds_write2st64_b32 v157, v7, v9 offset0:18 offset1:19
	ds_write2st64_b32 v157, v10, v12 offset0:4 offset1:5
	ds_write2st64_b32 v157, v11, v13 offset0:20 offset1:21
	ds_write2st64_b32 v157, v14, v16 offset0:6 offset1:7
	ds_write2st64_b32 v157, v15, v17 offset0:22 offset1:23
	ds_write2st64_b32 v157, v18, v20 offset0:8 offset1:9
	ds_write2st64_b32 v157, v19, v21 offset0:24 offset1:25
	ds_write2st64_b32 v157, v22, v24 offset0:10 offset1:11
	ds_write2st64_b32 v157, v23, v25 offset0:26 offset1:27
	ds_write2st64_b32 v157, v26, v28 offset0:12 offset1:13
	ds_write2st64_b32 v157, v27, v29 offset0:28 offset1:29
	ds_write2st64_b32 v157, v32, v33 offset0:14 offset1:15
	ds_write2st64_b32 v157, v30, v1 offset0:30 offset1:31
	v_mov_b32_e32 v1, 0
	s_mov_b64 s[0:1], exec
	v_readlane_b32 s2, v254, 54
	v_readlane_b32 s3, v254, 55
	s_and_b64 s[2:3], s[0:1], s[2:3]
	s_mov_b64 exec, s[2:3]
	ds_read_b32 v1, v160
	s_or_b64 exec, exec, s[0:1]
	v_ashrrev_i32_e32 v2, 6, v176
	v_readlane_b32 s0, v254, 52
	v_add_u32_e32 v3, -1, v2
	v_cmp_eq_u32_e32 vcc, v146, v2
	v_readlane_b32 s1, v254, 53
	s_or_b64 s[0:1], s[0:1], vcc
	v_cmp_eq_u32_e32 vcc, v146, v3
	s_or_b64 s[0:1], s[0:1], vcc
	v_cmp_le_i32_e32 vcc, v146, v2
	s_and_b64 s[2:3], vcc, s[0:1]
	s_xor_b64 s[0:1], s[0:1], -1
	s_and_b64 s[54:55], vcc, s[0:1]
	v_cmp_eq_u32_e32 vcc, v158, v2
	v_cmp_eq_u32_e64 s[0:1], v158, v3
	s_or_b64 s[0:1], vcc, s[0:1]
	v_cmp_le_i32_e32 vcc, v158, v2
	ds_read_b128 v[2:5], v159
	ds_read2_b32 v[6:7], v161 offset0:1 offset1:2
	s_and_b64 s[6:7], vcc, s[0:1]
	s_xor_b64 s[0:1], s[0:1], -1
	s_and_b64 s[52:53], vcc, s[0:1]
	s_waitcnt lgkmcnt(1)
	v_fmac_f32_e32 v1, 2.0, v2
	v_fmac_f32_e32 v1, 2.0, v3
	ds_read2_b32 v[2:3], v171 offset1:1
	v_fmac_f32_e32 v1, 2.0, v4
	v_add_f32_e32 v1, v5, v1
	v_cndmask_b32_e64 v4, 0, v1, s[54:55]
	ds_read_b32 v1, v161 offset:12
	s_waitcnt lgkmcnt(1)
	v_fmac_f32_e32 v2, 2.0, v3
	v_fmac_f32_e32 v2, 2.0, v6
	v_fmac_f32_e32 v2, 2.0, v7
	s_xor_b64 s[8:9], s[2:3], -1
	s_waitcnt lgkmcnt(0)
	v_add_f32_e32 v1, v1, v2
	v_cndmask_b32_e64 v3, 0, v1, s[52:53]
	v_cndmask_b32_e64 v1, 0, 1, s[2:3]
	v_cmp_ne_u32_e32 vcc, 0, v1
	v_cndmask_b32_e64 v2, 0, 1, s[6:7]
	s_bcnt1_i32_b64 s0, vcc
	v_cmp_ne_u32_e32 vcc, 0, v2
	s_bcnt1_i32_b64 s1, vcc
	s_add_i32 s0, s0, s1
	s_mov_b32 s14, 0
	s_sub_i32 s15, 16, s0
	s_mov_b32 s0, 30

.LBB0_382:
	s_waitcnt vmcnt(0) lgkmcnt(0)
	s_barrier
	v_mov_b32_e32 v34, v169
	ds_bpermute_b32 v1, v150, v143
	v_readfirstlane_b32 s5, v170
	global_load_dword v169, v[124:125], off offset:128
	s_waitcnt lgkmcnt(0)
	v_add_f32_e32 v1, v143, v1
	v_max_f32_e32 v1, 0xda24260, v1
	v_div_scale_f32 v35, s[0:1], v1, v1, v34
	v_rcp_f32_e32 v36, v35
	s_add_u32 s0, s16, 0x2000000
	s_addc_u32 s1, s17, 0
	s_add_i32 s2, s12, 0xfffffe01
	v_fma_f32 v37, -v35, v36, 1.0
	v_fmac_f32_e32 v36, v37, v36
	v_div_scale_f32 v37, vcc, v34, v1, v34
	v_mul_f32_e32 v38, v37, v36
	v_fma_f32 v39, -v35, v38, v37
	v_fmac_f32_e32 v38, v39, v36
	v_fma_f32 v35, -v35, v38, v37
	v_div_fmas_f32 v35, v35, v36, v38
	ds_read2st64_b32 v[36:37], v156 offset0:16 offset1:17
	v_div_fixup_f32 v1, v35, v1, v34
	ds_read2st64_b32 v[34:35], v156 offset1:1
	s_and_b32 s2, s2, 0xffffff80
	s_cmpk_gt_i32 s12, 0x1fe
	s_waitcnt lgkmcnt(1)
	v_fma_f32 v2, v2, v1, v36
	v_fmac_f32_e32 v37, v3, v1
	ds_write2st64_b32 v156, v2, v37 offset0:16 offset1:17
	ds_read2st64_b32 v[2:3], v156 offset0:2 offset1:3
	s_waitcnt lgkmcnt(2)
	v_fma_f32 v18, v18, v1, v34
	v_fmac_f32_e32 v35, v19, v1
	ds_write2st64_b32 v156, v18, v35 offset1:1
	ds_read2st64_b32 v[18:19], v156 offset0:18 offset1:19
	s_waitcnt lgkmcnt(2)
	v_fma_f32 v2, v20, v1, v2
	v_fmac_f32_e32 v3, v21, v1
	ds_write2st64_b32 v156, v2, v3 offset0:2 offset1:3
	ds_read2st64_b32 v[2:3], v156 offset0:4 offset1:5
	s_waitcnt lgkmcnt(2)
	v_fma_f32 v4, v4, v1, v18
	v_fmac_f32_e32 v19, v5, v1
	ds_write2st64_b32 v156, v4, v19 offset0:18 offset1:19
	ds_read2st64_b32 v[4:5], v156 offset0:20 offset1:21
	s_waitcnt lgkmcnt(2)
	v_fma_f32 v2, v22, v1, v2
	v_fmac_f32_e32 v3, v23, v1
	ds_write2st64_b32 v156, v2, v3 offset0:4 offset1:5
	ds_read2st64_b32 v[2:3], v156 offset0:6 offset1:7
	s_waitcnt lgkmcnt(2)
	v_fma_f32 v4, v6, v1, v4
	v_fmac_f32_e32 v5, v7, v1
	ds_write2st64_b32 v156, v4, v5 offset0:20 offset1:21
	ds_read2st64_b32 v[4:5], v156 offset0:22 offset1:23
	s_waitcnt lgkmcnt(2)
	v_fma_f32 v2, v24, v1, v2
	v_fmac_f32_e32 v3, v25, v1
	ds_write2st64_b32 v156, v2, v3 offset0:6 offset1:7
	ds_read2st64_b32 v[2:3], v156 offset0:8 offset1:9
	s_waitcnt lgkmcnt(2)
	v_fma_f32 v4, v8, v1, v4
	v_fmac_f32_e32 v5, v9, v1
	ds_write2st64_b32 v156, v4, v5 offset0:22 offset1:23
	ds_read2st64_b32 v[4:5], v156 offset0:24 offset1:25
	s_waitcnt lgkmcnt(2)
	v_fma_f32 v2, v26, v1, v2
	v_fmac_f32_e32 v3, v27, v1
	ds_write2st64_b32 v156, v2, v3 offset0:8 offset1:9
	ds_read2st64_b32 v[2:3], v156 offset0:10 offset1:11
	s_waitcnt lgkmcnt(2)
	v_fma_f32 v4, v10, v1, v4
	v_fmac_f32_e32 v5, v11, v1
	ds_write2st64_b32 v156, v4, v5 offset0:24 offset1:25
	ds_read2st64_b32 v[4:5], v156 offset0:26 offset1:27
	s_waitcnt lgkmcnt(2)
	v_fma_f32 v2, v28, v1, v2
	v_fmac_f32_e32 v3, v29, v1
	ds_write2st64_b32 v156, v2, v3 offset0:10 offset1:11
	ds_read2st64_b32 v[2:3], v156 offset0:12 offset1:13
	s_waitcnt lgkmcnt(2)
	v_fma_f32 v4, v12, v1, v4
	v_fmac_f32_e32 v5, v13, v1
	ds_write2st64_b32 v156, v4, v5 offset0:26 offset1:27
	ds_read2st64_b32 v[4:5], v156 offset0:28 offset1:29
	s_waitcnt lgkmcnt(2)
	v_fma_f32 v2, v30, v1, v2
	v_fmac_f32_e32 v3, v31, v1
	ds_write2st64_b32 v156, v2, v3 offset0:12 offset1:13
	ds_read2st64_b32 v[2:3], v156 offset0:14 offset1:15
	s_waitcnt lgkmcnt(2)
	v_fma_f32 v4, v14, v1, v4
	v_fmac_f32_e32 v5, v15, v1
	ds_write2st64_b32 v156, v4, v5 offset0:28 offset1:29
	ds_read2st64_b32 v[4:5], v156 offset0:30 offset1:31
	s_cselect_b32 s82, s2, 0
	s_add_u32 s2, s16, 0x2800000
	s_addc_u32 s3, s17, 0
	s_ashr_i32 s4, s5, 6
	s_cmp_lt_i32 s4, 36
	s_waitcnt lgkmcnt(2)
	v_fma_f32 v2, v32, v1, v2
	s_waitcnt lgkmcnt(0)
	v_fma_f32 v4, v16, v1, v4
	v_fmac_f32_e32 v3, v33, v1
	v_fmac_f32_e32 v5, v17, v1
	s_cselect_b64 s[40:41], -1, 0
	s_cmp_gt_i32 s4, 35
	ds_write2st64_b32 v156, v2, v3 offset0:14 offset1:15
	ds_write2st64_b32 v156, v4, v5 offset0:30 offset1:31
	s_cbranch_scc0 .LBB0_413
	s_cmp_lt_i32 s4, 28
	s_cselect_b64 s[64:65], -1, 0
	s_cmp_gt_i32 s4, 27
	s_cbranch_scc0 .LBB0_414
